# strategy 4: static s_setprio 1 for the RWKV scan waves (waves 0-3) for the whole scan phase
# speedup vs baseline: 1.0104x; 1.0104x over previous
; __device__ __forceinline__ int ltid() { int t = threadIdx.x; asm volatile("" : "+v"(t)); return t; }
; __device__ __forceinline__ int lsg(int x) { x = __builtin_amdgcn_readfirstlane(x); asm volatile("" : "+s"(x)); return x; }
; __device__ __forceinline__ void phase_rwkv(KP P, int l_, unsigned char* shm) {
;     const int l = lsg(l_);
;     const int tid = ltid(), wave = __builtin_amdgcn_readfirstlane(tid >> 6), lane = tid & 63;
;     const int rp = (tid & 255) >> 3, seg = tid & 7, pw = wave & 3;
;     const bool scanw = wave < 4;
.LBB0_2460:
	s_or_b64 exec, exec, s[4:5]
	v_readlane_b32 s0, v255, 1
	s_mov_b32 s4, s0
	v_readlane_b32 s0, v254, 1
	s_mov_b64 s[6:7], s[72:73]
	s_waitcnt lgkmcnt(0)
	v_mov_b32_e32 v0, v228
	v_readlane_b32 s1, v254, 2
	s_barrier
	s_and_b64 vcc, exec, s[0:1]
	v_readfirstlane_b32 s5, v0
	s_cbranch_vccz .LBB0_2529
	s_load_dwordx2 s[8:9], s[6:7], 0xf8
	s_load_dwordx2 s[22:23], s[6:7], 0xc0
	s_ashr_i32 s0, s5, 6
	s_cmp_gt_i32 s0, 3
	s_cselect_b64 s[20:21], -1, 0
	s_cbranch_scc1 .Lrw_prio_skip
	s_setprio 1
